# qkconv conv loop: next-trip prefetch (two register sets, unrolled by 2, scalar trip control) on top of hoisted conv weights
# speedup vs baseline: 1.0106x; 1.0039x over previous
.LBB0_1608:
	s_or_b64 exec, exec, s[18:19]
	v_lshl_add_u32 v2, s2, 9, v128
	s_mov_b32 s0, 0x240000
	v_cmp_gt_i32_e32 vcc, s0, v2
	s_and_saveexec_b64 s[6:7], vcc
	v_readlane_b32 s36, v252, 16
	v_readlane_b32 s50, v252, 30
	v_readlane_b32 s51, v252, 31
	v_readlane_b32 s37, v252, 17
	v_readlane_b32 s38, v252, 18
	v_readlane_b32 s39, v252, 19
	v_readlane_b32 s40, v252, 20
	v_readlane_b32 s41, v252, 21
	v_readlane_b32 s42, v252, 22
	v_readlane_b32 s43, v252, 23
	v_readlane_b32 s44, v252, 24
	v_readlane_b32 s45, v252, 25
	v_readlane_b32 s46, v252, 26
	v_readlane_b32 s47, v252, 27
	v_readlane_b32 s48, v252, 28
	v_readlane_b32 s49, v252, 29
	s_cbranch_execz .LBB0_1611
	v_lshlrev_b32_e32 v0, 3, v128
	s_mov_b64 s[26:27], s[50:51]
	s_lshl_b32 s14, s22, 9
	v_lshl_add_u32 v3, s2, 12, v0
	s_lshl_b32 s15, s22, 12
	s_mov_b64 s[8:9], 0
	s_movk_i32 s16, 0x4000
	s_waitcnt vmcnt(2)
	v_mov_b32_e32 v4, 0xff
	v_mov_b32_e32 v5, 0x7ff
	v_mov_b32_e32 v6, 0x100
	v_mov_b32_e32 v7, 0x800
	v_mov_b32_e32 v1, 0
	s_mov_b64 s[10:11], 0x1000
	s_mov_b64 s[12:13], 0x2000
	s_movk_i32 s17, 0x2000
	s_movk_i32 s18, 0x1ff
	v_mov_b32_e32 v8, 0x3e000000
	s_mov_b32 s19, 0x23ffff
	v_and_b32_e32 v9, 0x3f8, v3
	v_lshlrev_b32_e32 v0, 2, v9
	v_add_u32_e32 v106, 0x1000, v0
	v_add_u32_e32 v107, 0x2000, v0
	global_load_dwordx4 v[74:77], v0, s[72:73]
	global_load_dwordx4 v[78:81], v0, s[72:73] offset:16
	global_load_dwordx4 v[82:85], v0, s[26:27]
	global_load_dwordx4 v[86:89], v0, s[26:27] offset:16
	global_load_dwordx4 v[90:93], v106, s[26:27]
	global_load_dwordx4 v[94:97], v106, s[26:27] offset:16
	global_load_dwordx4 v[98:101], v107, s[26:27]
	global_load_dwordx4 v[102:105], v107, s[26:27] offset:16
	v_lshlrev_b32_e32 v68, 1, v9
	v_mov_b32_e32 v69, v1
	v_cmp_lt_u32_e64 s[0:1], s18, v9
	v_lshl_add_u64 v[70:71], s[88:89], 0, v[68:69]
	v_lshl_add_u64 v[68:69], s[4:5], 0, v[68:69]
	v_cndmask_b32_e64 v67, 1.0, v8, s[0:1]
	s_lshl_b32 s98, s2, 9
	v_ashrrev_i32_e32 v26, 7, v2
	v_cmp_gt_i32_e32 vcc, s16, v26
	v_ashrrev_i32_e32 v27, 31, v26
	v_lshlrev_b64 v[30:31], 11, v[26:27]
	v_cndmask_b32_e32 v14, v4, v5, vcc
	v_cndmask_b32_e32 v33, v6, v7, vcc
	v_and_b32_e32 v32, v14, v26
	v_add_u32_e32 v34, -1, v33
	v_add_u32_e32 v0, -1, v32
	v_add_u32_e32 v36, 1, v32
	v_sub_u32_e32 v35, v26, v32
	v_cmp_lt_u32_e32 vcc, v32, v33
	v_min_u32_e32 v37, v32, v34
	v_min_u32_e32 v38, v36, v34
	v_cndmask_b32_e64 v56, 0, 1.0, vcc
	v_cmp_lt_u32_e32 vcc, v0, v33
	v_max_i32_e32 v0, 0, v0
	v_min_u32_e32 v0, v0, v34
	v_cndmask_b32_e64 v57, 0, 1.0, vcc
	v_cmp_lt_u32_e32 vcc, v36, v33
	v_add_u32_e32 v16, v35, v37
	v_add_u32_e32 v18, v38, v35
	v_cndmask_b32_e64 v58, 0, 1.0, vcc
	v_add_u32_e32 v20, v0, v35
	v_ashrrev_i32_e32 v17, 31, v16
	v_ashrrev_i32_e32 v19, 31, v18
	v_ashrrev_i32_e32 v21, 31, v20
	v_lshlrev_b64 v[16:17], 11, v[16:17]
	v_lshlrev_b64 v[18:19], 11, v[18:19]
	v_lshlrev_b64 v[20:21], 11, v[20:21]
	v_lshl_add_u64 v[108:109], v[68:69], 0, v[20:21]
	v_lshl_add_u64 v[110:111], v[68:69], 0, v[16:17]
	v_lshl_add_u64 v[112:113], v[68:69], 0, v[18:19]
	v_lshl_add_u64 v[54:55], v[70:71], 0, v[30:31]
	global_load_dwordx4 v[46:49], v[108:109], off
	global_load_dwordx4 v[50:53], v[110:111], off
	global_load_dwordx4 v[42:45], v[112:113], off
	v_add_u32_e32 v2, s14, v2
	s_add_i32 s98, s98, s14
	s_cmp_lt_i32 s98, 0x240000
	s_cbranch_scc0 .Lqkc_tail_x
	v_ashrrev_i32_e32 v26, 7, v2
	v_cmp_gt_i32_e32 vcc, s16, v26
	v_ashrrev_i32_e32 v27, 31, v26
	v_lshlrev_b64 v[30:31], 11, v[26:27]
	v_cndmask_b32_e32 v14, v4, v5, vcc
	v_cndmask_b32_e32 v33, v6, v7, vcc
	v_and_b32_e32 v32, v14, v26
	v_add_u32_e32 v34, -1, v33
	v_add_u32_e32 v0, -1, v32
	v_add_u32_e32 v36, 1, v32
	v_sub_u32_e32 v35, v26, v32
	v_cmp_lt_u32_e32 vcc, v32, v33
	v_min_u32_e32 v37, v32, v34
	v_min_u32_e32 v38, v36, v34
	v_cndmask_b32_e64 v126, 0, 1.0, vcc
	v_cmp_lt_u32_e32 vcc, v0, v33
	v_max_i32_e32 v0, 0, v0
	v_min_u32_e32 v0, v0, v34
	v_cndmask_b32_e64 v127, 0, 1.0, vcc
	v_cmp_lt_u32_e32 vcc, v36, v33
	v_add_u32_e32 v16, v35, v37
	v_add_u32_e32 v18, v38, v35
	v_cndmask_b32_e64 v73, 0, 1.0, vcc
	v_add_u32_e32 v20, v0, v35
	v_ashrrev_i32_e32 v17, 31, v16
	v_ashrrev_i32_e32 v19, 31, v18
	v_ashrrev_i32_e32 v21, 31, v20
	v_lshlrev_b64 v[16:17], 11, v[16:17]
	v_lshlrev_b64 v[18:19], 11, v[18:19]
	v_lshlrev_b64 v[20:21], 11, v[20:21]
	v_lshl_add_u64 v[108:109], v[68:69], 0, v[20:21]
	v_lshl_add_u64 v[110:111], v[68:69], 0, v[16:17]
	v_lshl_add_u64 v[112:113], v[68:69], 0, v[18:19]
	v_lshl_add_u64 v[106:107], v[70:71], 0, v[30:31]
	global_load_dwordx4 v[114:117], v[108:109], off
	global_load_dwordx4 v[118:121], v[110:111], off
	global_load_dwordx4 v[122:125], v[112:113], off
	v_add_u32_e32 v2, s14, v2
	s_add_i32 s98, s98, s14
	s_waitcnt vmcnt(3)
.Lqkc_loop:
	s_waitcnt vmcnt(6)
	v_mul_f32_e32 v18, v57, v82
	v_mul_f32_e32 v19, v57, v83
	v_mul_f32_e32 v20, v57, v84
	v_mul_f32_e32 v21, v57, v85
	v_mul_f32_e32 v22, v57, v86
	v_mul_f32_e32 v23, v57, v87
	v_mul_f32_e32 v24, v57, v88
	v_mul_f32_e32 v25, v57, v89
	v_lshlrev_b32_e32 v59, 16, v46
	v_and_b32_e32 v60, 0xffff0000, v46
	v_lshlrev_b32_e32 v61, 16, v47
	v_and_b32_e32 v62, 0xffff0000, v47
	v_lshlrev_b32_e32 v63, 16, v48
	v_and_b32_e32 v64, 0xffff0000, v48
	v_lshlrev_b32_e32 v65, 16, v49
	v_and_b32_e32 v66, 0xffff0000, v49
	v_fma_f32 v10, v18, v59, v74
	v_fma_f32 v11, v19, v60, v75
	v_fma_f32 v12, v20, v61, v76
	v_fma_f32 v13, v21, v62, v77
	v_fma_f32 v14, v22, v63, v78
	v_fma_f32 v15, v23, v64, v79
	v_fma_f32 v16, v24, v65, v80
	v_fma_f32 v17, v25, v66, v81
	s_waitcnt vmcnt(5)
	v_mul_f32_e32 v26, v56, v90
	v_mul_f32_e32 v27, v56, v91
	v_mul_f32_e32 v28, v56, v92
	v_mul_f32_e32 v29, v56, v93
	v_mul_f32_e32 v30, v56, v94
	v_mul_f32_e32 v31, v56, v95
	v_mul_f32_e32 v32, v56, v96
	v_mul_f32_e32 v33, v56, v97
	v_lshlrev_b32_e32 v59, 16, v50
	v_and_b32_e32 v60, 0xffff0000, v50
	v_lshlrev_b32_e32 v61, 16, v51
	v_and_b32_e32 v62, 0xffff0000, v51
	v_lshlrev_b32_e32 v63, 16, v52
	v_and_b32_e32 v64, 0xffff0000, v52
	v_lshlrev_b32_e32 v65, 16, v53
	v_and_b32_e32 v66, 0xffff0000, v53
	v_fmac_f32_e32 v10, v26, v59
	v_fmac_f32_e32 v11, v27, v60
	v_fmac_f32_e32 v12, v28, v61
	v_fmac_f32_e32 v13, v29, v62
	v_fmac_f32_e32 v14, v30, v63
	v_fmac_f32_e32 v15, v31, v64
	v_fmac_f32_e32 v16, v32, v65
	v_fmac_f32_e32 v17, v33, v66
	s_waitcnt vmcnt(4)
	v_mul_f32_e32 v34, v58, v98
	v_mul_f32_e32 v35, v58, v99
	v_mul_f32_e32 v36, v58, v100
	v_mul_f32_e32 v37, v58, v101
	v_mul_f32_e32 v38, v58, v102
	v_mul_f32_e32 v39, v58, v103
	v_mul_f32_e32 v40, v58, v104
	v_mul_f32_e32 v41, v58, v105
	v_lshlrev_b32_e32 v59, 16, v42
	v_and_b32_e32 v60, 0xffff0000, v42
	v_lshlrev_b32_e32 v61, 16, v43
	v_and_b32_e32 v62, 0xffff0000, v43
	v_lshlrev_b32_e32 v63, 16, v44
	v_and_b32_e32 v64, 0xffff0000, v44
	v_lshlrev_b32_e32 v65, 16, v45
	v_and_b32_e32 v66, 0xffff0000, v45
	v_fmac_f32_e32 v10, v34, v59
	v_fmac_f32_e32 v11, v35, v60
	v_fmac_f32_e32 v12, v36, v61
	v_fmac_f32_e32 v13, v37, v62
	v_fmac_f32_e32 v14, v38, v63
	v_fmac_f32_e32 v15, v39, v64
	v_fmac_f32_e32 v16, v40, v65
	v_fmac_f32_e32 v17, v41, v66
	v_mul_f32_e32 v18, 0xbfb8aa3b, v10
	v_mul_f32_e32 v19, 0xbfb8aa3b, v11
	v_mul_f32_e32 v20, 0xbfb8aa3b, v12
	v_mul_f32_e32 v21, 0xbfb8aa3b, v13
	v_mul_f32_e32 v22, 0xbfb8aa3b, v14
	v_mul_f32_e32 v23, 0xbfb8aa3b, v15
	v_mul_f32_e32 v24, 0xbfb8aa3b, v16
	v_mul_f32_e32 v25, 0xbfb8aa3b, v17
	v_exp_f32_e32 v18, v18
	v_exp_f32_e32 v19, v19
	v_exp_f32_e32 v20, v20
	v_exp_f32_e32 v21, v21
	v_exp_f32_e32 v22, v22
	v_exp_f32_e32 v23, v23
	v_exp_f32_e32 v24, v24
	v_exp_f32_e32 v25, v25
	v_add_f32_e32 v18, 1.0, v18
	v_add_f32_e32 v19, 1.0, v19
	v_add_f32_e32 v20, 1.0, v20
	v_add_f32_e32 v21, 1.0, v21
	v_add_f32_e32 v22, 1.0, v22
	v_add_f32_e32 v23, 1.0, v23
	v_add_f32_e32 v24, 1.0, v24
	v_add_f32_e32 v25, 1.0, v25
	v_rcp_f32_e32 v18, v18
	v_rcp_f32_e32 v19, v19
	v_rcp_f32_e32 v20, v20
	v_rcp_f32_e32 v21, v21
	v_rcp_f32_e32 v22, v22
	v_rcp_f32_e32 v23, v23
	v_rcp_f32_e32 v24, v24
	v_rcp_f32_e32 v25, v25
	v_mul_f32_e32 v18, v10, v18
	v_mul_f32_e32 v19, v11, v19
	v_mul_f32_e32 v20, v12, v20
	v_mul_f32_e32 v21, v13, v21
	v_mul_f32_e32 v22, v14, v22
	v_mul_f32_e32 v23, v15, v23
	v_mul_f32_e32 v24, v16, v24
	v_mul_f32_e32 v25, v17, v25
	v_mul_f32_e32 v18, v67, v18
	v_mul_f32_e32 v19, v67, v19
	v_mul_f32_e32 v20, v67, v20
	v_mul_f32_e32 v21, v67, v21
	v_mul_f32_e32 v22, v67, v22
	v_mul_f32_e32 v23, v67, v23
	v_mul_f32_e32 v24, v67, v24
	v_mul_f32_e32 v25, v67, v25
	v_cvt_pk_bf16_f32 v10, v18, v19
	v_cvt_pk_bf16_f32 v11, v20, v21
	v_cvt_pk_bf16_f32 v12, v22, v23
	v_cvt_pk_bf16_f32 v13, v24, v25
	global_store_dwordx4 v[54:55], v[10:13], off
	s_cmp_lt_i32 s98, 0x240000
	s_cbranch_scc0 .Lqkc_tail_y
	v_ashrrev_i32_e32 v26, 7, v2
	v_cmp_gt_i32_e32 vcc, s16, v26
	v_ashrrev_i32_e32 v27, 31, v26
	v_lshlrev_b64 v[30:31], 11, v[26:27]
	v_cndmask_b32_e32 v14, v4, v5, vcc
	v_cndmask_b32_e32 v33, v6, v7, vcc
	v_and_b32_e32 v32, v14, v26
	v_add_u32_e32 v34, -1, v33
	v_add_u32_e32 v0, -1, v32
	v_add_u32_e32 v36, 1, v32
	v_sub_u32_e32 v35, v26, v32
	v_cmp_lt_u32_e32 vcc, v32, v33
	v_min_u32_e32 v37, v32, v34
	v_min_u32_e32 v38, v36, v34
	v_cndmask_b32_e64 v56, 0, 1.0, vcc
	v_cmp_lt_u32_e32 vcc, v0, v33
	v_max_i32_e32 v0, 0, v0
	v_min_u32_e32 v0, v0, v34
	v_cndmask_b32_e64 v57, 0, 1.0, vcc
	v_cmp_lt_u32_e32 vcc, v36, v33
	v_add_u32_e32 v16, v35, v37
	v_add_u32_e32 v18, v38, v35
	v_cndmask_b32_e64 v58, 0, 1.0, vcc
	v_add_u32_e32 v20, v0, v35
	v_ashrrev_i32_e32 v17, 31, v16
	v_ashrrev_i32_e32 v19, 31, v18
	v_ashrrev_i32_e32 v21, 31, v20
	v_lshlrev_b64 v[16:17], 11, v[16:17]
	v_lshlrev_b64 v[18:19], 11, v[18:19]
	v_lshlrev_b64 v[20:21], 11, v[20:21]
	v_lshl_add_u64 v[108:109], v[68:69], 0, v[20:21]
	v_lshl_add_u64 v[110:111], v[68:69], 0, v[16:17]
	v_lshl_add_u64 v[112:113], v[68:69], 0, v[18:19]
	v_lshl_add_u64 v[54:55], v[70:71], 0, v[30:31]
	global_load_dwordx4 v[46:49], v[108:109], off
	global_load_dwordx4 v[50:53], v[110:111], off
	global_load_dwordx4 v[42:45], v[112:113], off
	v_add_u32_e32 v2, s14, v2
	s_add_i32 s98, s98, s14
	s_waitcnt vmcnt(6)
	v_mul_f32_e32 v18, v127, v82
	v_mul_f32_e32 v19, v127, v83
	v_mul_f32_e32 v20, v127, v84
	v_mul_f32_e32 v21, v127, v85
	v_mul_f32_e32 v22, v127, v86
	v_mul_f32_e32 v23, v127, v87
	v_mul_f32_e32 v24, v127, v88
	v_mul_f32_e32 v25, v127, v89
	v_lshlrev_b32_e32 v59, 16, v114
	v_and_b32_e32 v60, 0xffff0000, v114
	v_lshlrev_b32_e32 v61, 16, v115
	v_and_b32_e32 v62, 0xffff0000, v115
	v_lshlrev_b32_e32 v63, 16, v116
	v_and_b32_e32 v64, 0xffff0000, v116
	v_lshlrev_b32_e32 v65, 16, v117
	v_and_b32_e32 v66, 0xffff0000, v117
	v_fma_f32 v10, v18, v59, v74
	v_fma_f32 v11, v19, v60, v75
	v_fma_f32 v12, v20, v61, v76
	v_fma_f32 v13, v21, v62, v77
	v_fma_f32 v14, v22, v63, v78
	v_fma_f32 v15, v23, v64, v79
	v_fma_f32 v16, v24, v65, v80
	v_fma_f32 v17, v25, v66, v81
	s_waitcnt vmcnt(5)
	v_mul_f32_e32 v26, v126, v90
	v_mul_f32_e32 v27, v126, v91
	v_mul_f32_e32 v28, v126, v92
	v_mul_f32_e32 v29, v126, v93
	v_mul_f32_e32 v30, v126, v94
	v_mul_f32_e32 v31, v126, v95
	v_mul_f32_e32 v32, v126, v96
	v_mul_f32_e32 v33, v126, v97
	v_lshlrev_b32_e32 v59, 16, v118
	v_and_b32_e32 v60, 0xffff0000, v118
	v_lshlrev_b32_e32 v61, 16, v119
	v_and_b32_e32 v62, 0xffff0000, v119
	v_lshlrev_b32_e32 v63, 16, v120
	v_and_b32_e32 v64, 0xffff0000, v120
	v_lshlrev_b32_e32 v65, 16, v121
	v_and_b32_e32 v66, 0xffff0000, v121
	v_fmac_f32_e32 v10, v26, v59
	v_fmac_f32_e32 v11, v27, v60
	v_fmac_f32_e32 v12, v28, v61
	v_fmac_f32_e32 v13, v29, v62
	v_fmac_f32_e32 v14, v30, v63
	v_fmac_f32_e32 v15, v31, v64
	v_fmac_f32_e32 v16, v32, v65
	v_fmac_f32_e32 v17, v33, v66
	s_waitcnt vmcnt(4)
	v_mul_f32_e32 v34, v73, v98
	v_mul_f32_e32 v35, v73, v99
	v_mul_f32_e32 v36, v73, v100
	v_mul_f32_e32 v37, v73, v101
	v_mul_f32_e32 v38, v73, v102
	v_mul_f32_e32 v39, v73, v103
	v_mul_f32_e32 v40, v73, v104
	v_mul_f32_e32 v41, v73, v105
	v_lshlrev_b32_e32 v59, 16, v122
	v_and_b32_e32 v60, 0xffff0000, v122
	v_lshlrev_b32_e32 v61, 16, v123
	v_and_b32_e32 v62, 0xffff0000, v123
	v_lshlrev_b32_e32 v63, 16, v124
	v_and_b32_e32 v64, 0xffff0000, v124
	v_lshlrev_b32_e32 v65, 16, v125
	v_and_b32_e32 v66, 0xffff0000, v125
	v_fmac_f32_e32 v10, v34, v59
	v_fmac_f32_e32 v11, v35, v60
	v_fmac_f32_e32 v12, v36, v61
	v_fmac_f32_e32 v13, v37, v62
	v_fmac_f32_e32 v14, v38, v63
	v_fmac_f32_e32 v15, v39, v64
	v_fmac_f32_e32 v16, v40, v65
	v_fmac_f32_e32 v17, v41, v66
	v_mul_f32_e32 v18, 0xbfb8aa3b, v10
	v_mul_f32_e32 v19, 0xbfb8aa3b, v11
	v_mul_f32_e32 v20, 0xbfb8aa3b, v12
	v_mul_f32_e32 v21, 0xbfb8aa3b, v13
	v_mul_f32_e32 v22, 0xbfb8aa3b, v14
	v_mul_f32_e32 v23, 0xbfb8aa3b, v15
	v_mul_f32_e32 v24, 0xbfb8aa3b, v16
	v_mul_f32_e32 v25, 0xbfb8aa3b, v17
	v_exp_f32_e32 v18, v18
	v_exp_f32_e32 v19, v19
	v_exp_f32_e32 v20, v20
	v_exp_f32_e32 v21, v21
	v_exp_f32_e32 v22, v22
	v_exp_f32_e32 v23, v23
	v_exp_f32_e32 v24, v24
	v_exp_f32_e32 v25, v25
	v_add_f32_e32 v18, 1.0, v18
	v_add_f32_e32 v19, 1.0, v19
	v_add_f32_e32 v20, 1.0, v20
	v_add_f32_e32 v21, 1.0, v21
	v_add_f32_e32 v22, 1.0, v22
	v_add_f32_e32 v23, 1.0, v23
	v_add_f32_e32 v24, 1.0, v24
	v_add_f32_e32 v25, 1.0, v25
	v_rcp_f32_e32 v18, v18
	v_rcp_f32_e32 v19, v19
	v_rcp_f32_e32 v20, v20
	v_rcp_f32_e32 v21, v21
	v_rcp_f32_e32 v22, v22
	v_rcp_f32_e32 v23, v23
	v_rcp_f32_e32 v24, v24
	v_rcp_f32_e32 v25, v25
	v_mul_f32_e32 v18, v10, v18
	v_mul_f32_e32 v19, v11, v19
	v_mul_f32_e32 v20, v12, v20
	v_mul_f32_e32 v21, v13, v21
	v_mul_f32_e32 v22, v14, v22
	v_mul_f32_e32 v23, v15, v23
	v_mul_f32_e32 v24, v16, v24
	v_mul_f32_e32 v25, v17, v25
	v_mul_f32_e32 v18, v67, v18
	v_mul_f32_e32 v19, v67, v19
	v_mul_f32_e32 v20, v67, v20
	v_mul_f32_e32 v21, v67, v21
	v_mul_f32_e32 v22, v67, v22
	v_mul_f32_e32 v23, v67, v23
	v_mul_f32_e32 v24, v67, v24
	v_mul_f32_e32 v25, v67, v25
	v_cvt_pk_bf16_f32 v10, v18, v19
	v_cvt_pk_bf16_f32 v11, v20, v21
	v_cvt_pk_bf16_f32 v12, v22, v23
	v_cvt_pk_bf16_f32 v13, v24, v25
	global_store_dwordx4 v[106:107], v[10:13], off
	s_cmp_lt_i32 s98, 0x240000
	s_cbranch_scc0 .Lqkc_tail_x
	v_ashrrev_i32_e32 v26, 7, v2
	v_cmp_gt_i32_e32 vcc, s16, v26
	v_ashrrev_i32_e32 v27, 31, v26
	v_lshlrev_b64 v[30:31], 11, v[26:27]
	v_cndmask_b32_e32 v14, v4, v5, vcc
	v_cndmask_b32_e32 v33, v6, v7, vcc
	v_and_b32_e32 v32, v14, v26
	v_add_u32_e32 v34, -1, v33
	v_add_u32_e32 v0, -1, v32
	v_add_u32_e32 v36, 1, v32
	v_sub_u32_e32 v35, v26, v32
	v_cmp_lt_u32_e32 vcc, v32, v33
	v_min_u32_e32 v37, v32, v34
	v_min_u32_e32 v38, v36, v34
	v_cndmask_b32_e64 v126, 0, 1.0, vcc
	v_cmp_lt_u32_e32 vcc, v0, v33
	v_max_i32_e32 v0, 0, v0
	v_min_u32_e32 v0, v0, v34
	v_cndmask_b32_e64 v127, 0, 1.0, vcc
	v_cmp_lt_u32_e32 vcc, v36, v33
	v_add_u32_e32 v16, v35, v37
	v_add_u32_e32 v18, v38, v35
	v_cndmask_b32_e64 v73, 0, 1.0, vcc
	v_add_u32_e32 v20, v0, v35
	v_ashrrev_i32_e32 v17, 31, v16
	v_ashrrev_i32_e32 v19, 31, v18
	v_ashrrev_i32_e32 v21, 31, v20
	v_lshlrev_b64 v[16:17], 11, v[16:17]
	v_lshlrev_b64 v[18:19], 11, v[18:19]
	v_lshlrev_b64 v[20:21], 11, v[20:21]
	v_lshl_add_u64 v[108:109], v[68:69], 0, v[20:21]
	v_lshl_add_u64 v[110:111], v[68:69], 0, v[16:17]
	v_lshl_add_u64 v[112:113], v[68:69], 0, v[18:19]
	v_lshl_add_u64 v[106:107], v[70:71], 0, v[30:31]
	global_load_dwordx4 v[114:117], v[108:109], off
	global_load_dwordx4 v[118:121], v[110:111], off
	global_load_dwordx4 v[122:125], v[112:113], off
	v_add_u32_e32 v2, s14, v2
	s_add_i32 s98, s98, s14
	s_branch .Lqkc_loop
.Lqkc_tail_x:
	s_waitcnt vmcnt(0)
	v_mul_f32_e32 v18, v57, v82
	v_mul_f32_e32 v19, v57, v83
	v_mul_f32_e32 v20, v57, v84
	v_mul_f32_e32 v21, v57, v85
	v_mul_f32_e32 v22, v57, v86
	v_mul_f32_e32 v23, v57, v87
	v_mul_f32_e32 v24, v57, v88
	v_mul_f32_e32 v25, v57, v89
	v_lshlrev_b32_e32 v59, 16, v46
	v_and_b32_e32 v60, 0xffff0000, v46
	v_lshlrev_b32_e32 v61, 16, v47
	v_and_b32_e32 v62, 0xffff0000, v47
	v_lshlrev_b32_e32 v63, 16, v48
	v_and_b32_e32 v64, 0xffff0000, v48
	v_lshlrev_b32_e32 v65, 16, v49
	v_and_b32_e32 v66, 0xffff0000, v49
	v_fma_f32 v10, v18, v59, v74
	v_fma_f32 v11, v19, v60, v75
	v_fma_f32 v12, v20, v61, v76
	v_fma_f32 v13, v21, v62, v77
	v_fma_f32 v14, v22, v63, v78
	v_fma_f32 v15, v23, v64, v79
	v_fma_f32 v16, v24, v65, v80
	v_fma_f32 v17, v25, v66, v81
	v_mul_f32_e32 v26, v56, v90
	v_mul_f32_e32 v27, v56, v91
	v_mul_f32_e32 v28, v56, v92
	v_mul_f32_e32 v29, v56, v93
	v_mul_f32_e32 v30, v56, v94
	v_mul_f32_e32 v31, v56, v95
	v_mul_f32_e32 v32, v56, v96
	v_mul_f32_e32 v33, v56, v97
	v_lshlrev_b32_e32 v59, 16, v50
	v_and_b32_e32 v60, 0xffff0000, v50
	v_lshlrev_b32_e32 v61, 16, v51
	v_and_b32_e32 v62, 0xffff0000, v51
	v_lshlrev_b32_e32 v63, 16, v52
	v_and_b32_e32 v64, 0xffff0000, v52
	v_lshlrev_b32_e32 v65, 16, v53
	v_and_b32_e32 v66, 0xffff0000, v53
	v_fmac_f32_e32 v10, v26, v59
	v_fmac_f32_e32 v11, v27, v60
	v_fmac_f32_e32 v12, v28, v61
	v_fmac_f32_e32 v13, v29, v62
	v_fmac_f32_e32 v14, v30, v63
	v_fmac_f32_e32 v15, v31, v64
	v_fmac_f32_e32 v16, v32, v65
	v_fmac_f32_e32 v17, v33, v66
	v_mul_f32_e32 v34, v58, v98
	v_mul_f32_e32 v35, v58, v99
	v_mul_f32_e32 v36, v58, v100
	v_mul_f32_e32 v37, v58, v101
	v_mul_f32_e32 v38, v58, v102
	v_mul_f32_e32 v39, v58, v103
	v_mul_f32_e32 v40, v58, v104
	v_mul_f32_e32 v41, v58, v105
	v_lshlrev_b32_e32 v59, 16, v42
	v_and_b32_e32 v60, 0xffff0000, v42
	v_lshlrev_b32_e32 v61, 16, v43
	v_and_b32_e32 v62, 0xffff0000, v43
	v_lshlrev_b32_e32 v63, 16, v44
	v_and_b32_e32 v64, 0xffff0000, v44
	v_lshlrev_b32_e32 v65, 16, v45
	v_and_b32_e32 v66, 0xffff0000, v45
	v_fmac_f32_e32 v10, v34, v59
	v_fmac_f32_e32 v11, v35, v60
	v_fmac_f32_e32 v12, v36, v61
	v_fmac_f32_e32 v13, v37, v62
	v_fmac_f32_e32 v14, v38, v63
	v_fmac_f32_e32 v15, v39, v64
	v_fmac_f32_e32 v16, v40, v65
	v_fmac_f32_e32 v17, v41, v66
	v_mul_f32_e32 v18, 0xbfb8aa3b, v10
	v_mul_f32_e32 v19, 0xbfb8aa3b, v11
	v_mul_f32_e32 v20, 0xbfb8aa3b, v12
	v_mul_f32_e32 v21, 0xbfb8aa3b, v13
	v_mul_f32_e32 v22, 0xbfb8aa3b, v14
	v_mul_f32_e32 v23, 0xbfb8aa3b, v15
	v_mul_f32_e32 v24, 0xbfb8aa3b, v16
	v_mul_f32_e32 v25, 0xbfb8aa3b, v17
	v_exp_f32_e32 v18, v18
	v_exp_f32_e32 v19, v19
	v_exp_f32_e32 v20, v20
	v_exp_f32_e32 v21, v21
	v_exp_f32_e32 v22, v22
	v_exp_f32_e32 v23, v23
	v_exp_f32_e32 v24, v24
	v_exp_f32_e32 v25, v25
	v_add_f32_e32 v18, 1.0, v18
	v_add_f32_e32 v19, 1.0, v19
	v_add_f32_e32 v20, 1.0, v20
	v_add_f32_e32 v21, 1.0, v21
	v_add_f32_e32 v22, 1.0, v22
	v_add_f32_e32 v23, 1.0, v23
	v_add_f32_e32 v24, 1.0, v24
	v_add_f32_e32 v25, 1.0, v25
	v_rcp_f32_e32 v18, v18
	v_rcp_f32_e32 v19, v19
	v_rcp_f32_e32 v20, v20
	v_rcp_f32_e32 v21, v21
	v_rcp_f32_e32 v22, v22
	v_rcp_f32_e32 v23, v23
	v_rcp_f32_e32 v24, v24
	v_rcp_f32_e32 v25, v25
	v_mul_f32_e32 v18, v10, v18
	v_mul_f32_e32 v19, v11, v19
	v_mul_f32_e32 v20, v12, v20
	v_mul_f32_e32 v21, v13, v21
	v_mul_f32_e32 v22, v14, v22
	v_mul_f32_e32 v23, v15, v23
	v_mul_f32_e32 v24, v16, v24
	v_mul_f32_e32 v25, v17, v25
	v_mul_f32_e32 v18, v67, v18
	v_mul_f32_e32 v19, v67, v19
	v_mul_f32_e32 v20, v67, v20
	v_mul_f32_e32 v21, v67, v21
	v_mul_f32_e32 v22, v67, v22
	v_mul_f32_e32 v23, v67, v23
	v_mul_f32_e32 v24, v67, v24
	v_mul_f32_e32 v25, v67, v25
	v_cvt_pk_bf16_f32 v10, v18, v19
	v_cvt_pk_bf16_f32 v11, v20, v21
	v_cvt_pk_bf16_f32 v12, v22, v23
	v_cvt_pk_bf16_f32 v13, v24, v25
	global_store_dwordx4 v[54:55], v[10:13], off
	s_branch .LBB0_1611
.Lqkc_tail_y:
	s_waitcnt vmcnt(0)
	v_mul_f32_e32 v18, v127, v82
	v_mul_f32_e32 v19, v127, v83
	v_mul_f32_e32 v20, v127, v84
	v_mul_f32_e32 v21, v127, v85
	v_mul_f32_e32 v22, v127, v86
	v_mul_f32_e32 v23, v127, v87
	v_mul_f32_e32 v24, v127, v88
	v_mul_f32_e32 v25, v127, v89
	v_lshlrev_b32_e32 v59, 16, v114
	v_and_b32_e32 v60, 0xffff0000, v114
	v_lshlrev_b32_e32 v61, 16, v115
	v_and_b32_e32 v62, 0xffff0000, v115
	v_lshlrev_b32_e32 v63, 16, v116
	v_and_b32_e32 v64, 0xffff0000, v116
	v_lshlrev_b32_e32 v65, 16, v117
	v_and_b32_e32 v66, 0xffff0000, v117
	v_fma_f32 v10, v18, v59, v74
	v_fma_f32 v11, v19, v60, v75
	v_fma_f32 v12, v20, v61, v76
	v_fma_f32 v13, v21, v62, v77
	v_fma_f32 v14, v22, v63, v78
	v_fma_f32 v15, v23, v64, v79
	v_fma_f32 v16, v24, v65, v80
	v_fma_f32 v17, v25, v66, v81
	v_mul_f32_e32 v26, v126, v90
	v_mul_f32_e32 v27, v126, v91
	v_mul_f32_e32 v28, v126, v92
	v_mul_f32_e32 v29, v126, v93
	v_mul_f32_e32 v30, v126, v94
	v_mul_f32_e32 v31, v126, v95
	v_mul_f32_e32 v32, v126, v96
	v_mul_f32_e32 v33, v126, v97
	v_lshlrev_b32_e32 v59, 16, v118
	v_and_b32_e32 v60, 0xffff0000, v118
	v_lshlrev_b32_e32 v61, 16, v119
	v_and_b32_e32 v62, 0xffff0000, v119
	v_lshlrev_b32_e32 v63, 16, v120
	v_and_b32_e32 v64, 0xffff0000, v120
	v_lshlrev_b32_e32 v65, 16, v121
	v_and_b32_e32 v66, 0xffff0000, v121
	v_fmac_f32_e32 v10, v26, v59
	v_fmac_f32_e32 v11, v27, v60
	v_fmac_f32_e32 v12, v28, v61
	v_fmac_f32_e32 v13, v29, v62
	v_fmac_f32_e32 v14, v30, v63
	v_fmac_f32_e32 v15, v31, v64
	v_fmac_f32_e32 v16, v32, v65
	v_fmac_f32_e32 v17, v33, v66
	v_mul_f32_e32 v34, v73, v98
	v_mul_f32_e32 v35, v73, v99
	v_mul_f32_e32 v36, v73, v100
	v_mul_f32_e32 v37, v73, v101
	v_mul_f32_e32 v38, v73, v102
	v_mul_f32_e32 v39, v73, v103
	v_mul_f32_e32 v40, v73, v104
	v_mul_f32_e32 v41, v73, v105
	v_lshlrev_b32_e32 v59, 16, v122
	v_and_b32_e32 v60, 0xffff0000, v122
	v_lshlrev_b32_e32 v61, 16, v123
	v_and_b32_e32 v62, 0xffff0000, v123
	v_lshlrev_b32_e32 v63, 16, v124
	v_and_b32_e32 v64, 0xffff0000, v124
	v_lshlrev_b32_e32 v65, 16, v125
	v_and_b32_e32 v66, 0xffff0000, v125
	v_fmac_f32_e32 v10, v34, v59
	v_fmac_f32_e32 v11, v35, v60
	v_fmac_f32_e32 v12, v36, v61
	v_fmac_f32_e32 v13, v37, v62
	v_fmac_f32_e32 v14, v38, v63
	v_fmac_f32_e32 v15, v39, v64
	v_fmac_f32_e32 v16, v40, v65
	v_fmac_f32_e32 v17, v41, v66
	v_mul_f32_e32 v18, 0xbfb8aa3b, v10
	v_mul_f32_e32 v19, 0xbfb8aa3b, v11
	v_mul_f32_e32 v20, 0xbfb8aa3b, v12
	v_mul_f32_e32 v21, 0xbfb8aa3b, v13
	v_mul_f32_e32 v22, 0xbfb8aa3b, v14
	v_mul_f32_e32 v23, 0xbfb8aa3b, v15
	v_mul_f32_e32 v24, 0xbfb8aa3b, v16
	v_mul_f32_e32 v25, 0xbfb8aa3b, v17
	v_exp_f32_e32 v18, v18
	v_exp_f32_e32 v19, v19
	v_exp_f32_e32 v20, v20
	v_exp_f32_e32 v21, v21
	v_exp_f32_e32 v22, v22
	v_exp_f32_e32 v23, v23
	v_exp_f32_e32 v24, v24
	v_exp_f32_e32 v25, v25
	v_add_f32_e32 v18, 1.0, v18
	v_add_f32_e32 v19, 1.0, v19
	v_add_f32_e32 v20, 1.0, v20
	v_add_f32_e32 v21, 1.0, v21
	v_add_f32_e32 v22, 1.0, v22
	v_add_f32_e32 v23, 1.0, v23
	v_add_f32_e32 v24, 1.0, v24
	v_add_f32_e32 v25, 1.0, v25
	v_rcp_f32_e32 v18, v18
	v_rcp_f32_e32 v19, v19
	v_rcp_f32_e32 v20, v20
	v_rcp_f32_e32 v21, v21
	v_rcp_f32_e32 v22, v22
	v_rcp_f32_e32 v23, v23
	v_rcp_f32_e32 v24, v24
	v_rcp_f32_e32 v25, v25
	v_mul_f32_e32 v18, v10, v18
	v_mul_f32_e32 v19, v11, v19
	v_mul_f32_e32 v20, v12, v20
	v_mul_f32_e32 v21, v13, v21
	v_mul_f32_e32 v22, v14, v22
	v_mul_f32_e32 v23, v15, v23
	v_mul_f32_e32 v24, v16, v24
	v_mul_f32_e32 v25, v17, v25
	v_mul_f32_e32 v18, v67, v18
	v_mul_f32_e32 v19, v67, v19
	v_mul_f32_e32 v20, v67, v20
	v_mul_f32_e32 v21, v67, v21
	v_mul_f32_e32 v22, v67, v22
	v_mul_f32_e32 v23, v67, v23
	v_mul_f32_e32 v24, v67, v24
	v_mul_f32_e32 v25, v67, v25
	v_cvt_pk_bf16_f32 v10, v18, v19
	v_cvt_pk_bf16_f32 v11, v20, v21
	v_cvt_pk_bf16_f32 v12, v22, v23
	v_cvt_pk_bf16_f32 v13, v24, v25
	global_store_dwordx4 v[106:107], v[10:13], off
